# GEMM phase prologue de-serialised: both LDS-DMA staging groups (14 loads) issued before the first wait, vmcnt(2)->vmcnt(8); one memory round trip fewer per GEMM phase
# baseline (speedup 1.0000x reference)
.LBB0_169:
	v_readlane_b32 s2, v247, 52
	s_add_u32 s37, s2, s0
	v_readlane_b32 s0, v247, 53
	s_addc_u32 s39, s0, s1
	s_add_i32 m0, s31, 0x18000
	v_lshl_add_u64 v[0:1], v[0:1], 0, s[82:83]
	global_load_lds_dwordx4 v[0:1], off
	v_lshl_add_u64 v[0:1], v[2:3], 0, s[82:83]
	s_add_i32 m0, s31, 0x1a000
	s_add_i32 s47, s31, 0x8000
	global_load_lds_dwordx4 v[0:1], off
	v_lshl_add_u64 v[0:1], v[8:9], 0, s[82:83]
	s_mov_b32 m0, s47
	s_add_i32 s50, s31, 0xa000
	global_load_lds_dwordx4 v[0:1], off
	v_lshl_add_u64 v[0:1], v[10:11], 0, s[82:83]
	s_mov_b32 m0, s50
	v_bfe_u32 v18, v182, 4, 2
	global_load_lds_dwordx4 v[0:1], off
	s_add_i32 m0, s31, 0x1c000
	v_lshl_add_u64 v[0:1], v[4:5], 0, s[82:83]
	global_load_lds_dwordx4 v[0:1], off
	v_lshl_add_u64 v[0:1], v[6:7], 0, s[82:83]
	s_add_i32 m0, s31, 0x1e000
	v_and_b32_e32 v19, 15, v182
	global_load_lds_dwordx4 v[0:1], off
	s_waitcnt vmcnt(8)
	s_barrier
	v_lshlrev_b32_e32 v20, 4, v18
	v_lshl_or_b32 v183, s4, 6, v19
	v_lshl_or_b32 v19, v19, 6, v20
	v_lshlrev_b32_e32 v20, 2, v182
	s_lshl_b32 s0, s4, 13
	v_and_b32_e32 v20, 32, v20
	v_bitop3_b32 v21, v19, s0, v20 bitop3:0xde
	s_lshl_b32 s0, s5, 5
	v_add_u32_e32 v0, v17, v15
	s_lshr_b32 s46, s19, 6
	s_and_b32 s0, s0, 0x60
	v_add_lshl_u32 v0, v0, v16, 1
	v_mov_b32_e32 v1, v175
	s_lshl_b32 s1, s0, 7
	s_waitcnt vmcnt(6)
	s_add_i32 s51, s46, -2
	v_lshl_add_u64 v[186:187], s[78:79], 0, v[0:1]
	v_add_u32_e32 v0, v14, v12
	s_cmpk_lt_u32 s18, 0x100
	v_add_lshl_u32 v0, v0, v13, 1
	s_sext_i32_i8 s56, s20
	v_bitop3_b32 v192, s1, v19, v20 bitop3:0xf6
	s_cselect_b64 s[18:19], -1, 0
	s_and_b32 s73, s73, 0xffff
	v_lshl_or_b32 v193, v18, 2, s0
	v_lshl_add_u64 v[188:189], s[78:79], 0, v[0:1]
	s_mov_b32 s52, 0
	v_add_u32_e32 v194, 0, v21
	s_barrier
	s_mov_b32 s53, 0
	v_writelane_b32 v246, s53, 43
	s_branch .LBB0_172

.LBB0_232:
	s_cmp_lg_u64 s[48:49], 0
	s_cselect_b64 s[22:23], -1, 0
	s_and_b32 s73, s45, 0xffff
	s_cmp_eq_u32 s89, 1
	s_cselect_b64 s[24:25], -1, 0
	s_cmp_lg_u32 s89, 2
	s_cselect_b64 s[26:27], -1, 0
	s_and_b32 s62, s5, 3
	s_add_i32 m0, s19, 0x18000
	v_lshl_add_u64 v[0:1], v[0:1], 0, s[82:83]
	s_lshl_b32 s2, s4, 13
	s_lshl_b32 s38, s62, 5
	global_load_lds_dwordx4 v[0:1], off
	v_lshl_add_u64 v[0:1], v[2:3], 0, s[82:83]
	s_add_i32 m0, s19, 0x1a000
	s_add_i32 s39, s19, 0x8000
	s_add_i32 s46, s19, 0xa000
	v_lshl_or_b32 v163, s4, 6, v135
	global_load_lds_dwordx4 v[0:1], off
	v_lshl_add_u64 v[0:1], v[6:7], 0, s[82:83]
	s_mov_b32 m0, s39
	s_add_u32 s4, s8, 0x40080
	global_load_lds_dwordx4 v[0:1], off
	v_lshl_add_u64 v[0:1], v[4:5], 0, s[82:83]
	s_mov_b32 m0, s46
	s_addc_u32 s5, s9, 0
	global_load_lds_dwordx4 v[0:1], off
	s_add_i32 m0, s19, 0x1c000
	v_lshl_add_u64 v[0:1], s[4:5], 0, v[174:175]
	global_load_lds_dwordx4 v[0:1], off
	v_lshl_add_u64 v[0:1], s[4:5], 0, v[132:133]
	s_add_i32 m0, s19, 0x1e000
	s_cmpk_lt_u32 s12, 0x100
	global_load_lds_dwordx4 v[0:1], off
	s_waitcnt vmcnt(8)
	s_barrier
	s_cselect_b64 s[28:29], -1, 0
	s_abs_i32 s55, s69
	v_cvt_f32_u32_e32 v0, s55
	v_lshlrev_b32_e32 v9, 2, v135
	v_lshl_or_b32 v8, v135, 6, v158
	v_and_b32_e32 v9, 32, v9
	v_rcp_iflag_f32_e32 v0, v0
	v_bitop3_b32 v8, v8, s2, v9 bitop3:0xde
	s_sub_i32 s2, 0, s55
	s_waitcnt vmcnt(6)
	v_mul_f32_e32 v0, 0x4f7ffffe, v0
	v_cvt_u32_f32_e32 v0, v0
	s_mov_b32 s72, s44
	v_lshl_or_b32 v164, s62, 12, v159
	s_ashr_i32 s47, s69, 31
	v_readfirstlane_b32 s3, v0
	s_mul_i32 s2, s2, s3
	s_mul_hi_u32 s2, s3, s2
	s_mov_b32 s99, 0
	s_add_i32 s59, s3, s2
	v_add_u32_e32 v165, 0, v8
	v_writelane_b32 v246, s89, 27
	s_barrier
	s_mov_b32 s30, 0
	v_writelane_b32 v246, s30, 42
	s_branch .LBB0_235
